# MLA loop: one lgkmcnt wait per two MFMAs (reads are 6 deep), on top of prefetch depth 6
# speedup vs baseline: 1.0454x; 1.0079x over previous
.LBB0_859:
	ds_read_b128 v[236:239], v214 offset:8192
	ds_read_b128 v[240:243], v215 offset:8192
	ds_read_b128 v[244:247], v216 offset:8192
	ds_read_b128 v[248:251], v217 offset:8192
	ds_read_b128 v[252:255], v218 offset:8192
	ds_read_b128 v[176:179], v219 offset:8192
	v_exp_f32_e32 v97, v97
	v_exp_f32_e32 v99, v99
	v_exp_f32_e32 v100, v100
	v_exp_f32_e32 v101, v101
	v_exp_f32_e32 v102, v102
	v_exp_f32_e32 v103, v103
	v_exp_f32_e32 v106, v106
	v_exp_f32_e32 v107, v107
	s_waitcnt lgkmcnt(4)
	v_mfma_f32_32x32x16_bf16 v[80:95], v[236:239], v[144:147], v[64:79]
	ds_read_b128 v[180:183], v220 offset:8192
	v_exp_f32_e32 v108, v108
	v_exp_f32_e32 v109, v109
	v_exp_f32_e32 v110, v110
	v_exp_f32_e32 v111, v111
	v_mfma_f32_32x32x16_bf16 v[80:95], v[240:243], v[156:159], v[80:95]
	ds_read_b128 v[236:239], v221 offset:8192
	s_add_u32 s98, s34, s60
	s_addc_u32 s99, s35, s59
	s_add_u32 s98, s98, 0x140fc000
	s_addc_u32 s99, s99, 0
	s_add_u32 s100, s34, s62
	s_addc_u32 s101, s35, s61
	s_add_u32 s100, s100, 0x171b0100
	s_addc_u32 s101, s101, 0
	s_mov_b32 m0, s52
	s_cmp_lg_u64 s[24:25], 0
	s_cselect_b32 s4, s100, s98
	s_cselect_b32 s5, s101, s99
	global_load_lds_dwordx4 v190, s[4:5]
	s_mov_b32 m0, s53
	s_cmp_lg_u64 s[26:27], 0
	s_cselect_b32 s4, s100, s98
	s_cselect_b32 s5, s101, s99
	global_load_lds_dwordx4 v192, s[4:5]
	s_mov_b32 m0, s54
	s_cmp_lg_u64 s[28:29], 0
	s_cselect_b32 s4, s100, s98
	s_cselect_b32 s5, s101, s99
	global_load_lds_dwordx4 v194, s[4:5]
	s_mov_b32 m0, s55
	s_cmp_lg_u64 s[30:31], 0
	s_cselect_b32 s4, s100, s98
	s_cselect_b32 s5, s101, s99
	global_load_lds_dwordx4 v196, s[4:5]
	s_mov_b32 m0, s56
	s_cmp_lg_u64 s[6:7], 0
	s_cselect_b32 s4, s100, s98
	s_cselect_b32 s5, s101, s99
	global_load_lds_dwordx4 v198, s[4:5]
	s_waitcnt lgkmcnt(4)
	v_mfma_f32_32x32x16_bf16 v[80:95], v[244:247], v[168:171], v[80:95]
	ds_read_b128 v[240:243], v205 offset:53248
	v_mfma_f32_32x32x16_bf16 v[80:95], v[248:251], v[172:175], v[80:95]
	ds_read_b128 v[244:247], v207 offset:53248
	s_waitcnt lgkmcnt(4)
	v_mfma_f32_32x32x16_bf16 v[80:95], v[252:255], v[164:167], v[80:95]
	ds_read_b128 v[248:251], v209 offset:53248
	v_mfma_f32_32x32x16_bf16 v[80:95], v[176:179], v[160:163], v[80:95]
	ds_read_b128 v[252:255], v211 offset:53248
	s_waitcnt lgkmcnt(4)
	v_mfma_f32_32x32x16_bf16 v[80:95], v[180:183], v[152:155], v[80:95]
	ds_read_b128 v[176:179], v225
	v_mfma_f32_32x32x16_bf16 v[80:95], v[236:239], v[148:151], v[80:95]
	ds_read_b128 v[180:183], v225 offset:4096
	s_waitcnt lgkmcnt(4)
	v_mfma_f32_32x32x16_bf16 v[80:95], v[240:243], v[140:143], v[80:95]
	ds_read_b128 v[236:239], v225 offset:8192
	v_mfma_f32_32x32x16_bf16 v[80:95], v[244:247], v[136:139], v[80:95]
	ds_read_b128 v[240:243], v225 offset:12288
	s_waitcnt lgkmcnt(4)
	v_mfma_f32_32x32x16_bf16 v[80:95], v[248:251], v[132:135], v[80:95]
	ds_read_b128 v[244:247], v226
	v_mfma_f32_32x32x16_bf16 v[80:95], v[252:255], v[128:131], v[80:95]
	ds_read_b128 v[248:251], v226 offset:4096
	v_exp_f32_e32 v112, v96
	v_exp_f32_e32 v113, v98
	v_exp_f32_e32 v114, v104
	v_exp_f32_e32 v115, v105
	v_add_f32_e32 v96, 0, v112
	v_add_f32_e32 v96, v97, v96
	v_add_f32_e32 v96, v113, v96
	v_add_f32_e32 v96, v99, v96
	v_add_f32_e32 v96, v100, v96
	v_add_f32_e32 v96, v101, v96
	v_add_f32_e32 v96, v102, v96
	v_add_f32_e32 v96, v103, v96
	v_cvt_pk_bf16_f32 v100, v100, v101
	v_cvt_pk_bf16_f32 v101, v102, v103
	v_cvt_pk_bf16_f32 v98, v112, v97
	v_cvt_pk_bf16_f32 v99, v113, v99
	v_max_f32_e32 v97, v81, v81
	v_add_f32_e32 v96, v114, v96
	s_waitcnt lgkmcnt(4)
	v_mfma_f32_32x32x16_bf16 v[48:63], v[176:179], v[98:101], v[48:63]
	ds_read_b128 v[252:255], v226 offset:8192
	v_add_f32_e32 v96, v115, v96
	v_add_f32_e32 v96, v106, v96
	v_add_f32_e32 v96, v107, v96
	v_add_f32_e32 v96, v108, v96
	v_add_f32_e32 v96, v109, v96
	v_add_f32_e32 v96, v110, v96
	v_mfma_f32_32x32x16_bf16 v[32:47], v[180:183], v[98:101], v[32:47]
	ds_read_b128 v[176:179], v226 offset:12288
	v_add_f32_e32 v96, v111, v96
	v_add_f32_e32 v112, v230, v96
	s_waitcnt lgkmcnt(4)
	v_mfma_f32_32x32x16_bf16 v[16:31], v[236:239], v[98:101], v[16:31]
	ds_read_b128 v[180:183], v214 offset:16384
	v_mfma_f32_32x32x16_bf16 v[0:15], v[240:243], v[98:101], v[0:15]
	ds_read_b128 v[236:239], v215 offset:16384
	v_cvt_pk_bf16_f32 v98, v114, v115
	v_cvt_pk_bf16_f32 v99, v106, v107
	v_cvt_pk_bf16_f32 v100, v108, v109
	v_cvt_pk_bf16_f32 v101, v110, v111
	s_nop 0
	s_waitcnt lgkmcnt(4)
	v_mfma_f32_32x32x16_bf16 v[48:63], v[244:247], v[98:101], v[48:63]
	ds_read_b128 v[240:243], v216 offset:16384
	v_mfma_f32_32x32x16_bf16 v[32:47], v[248:251], v[98:101], v[32:47]
	ds_read_b128 v[244:247], v217 offset:16384
	s_waitcnt lgkmcnt(4)
	v_mfma_f32_32x32x16_bf16 v[16:31], v[252:255], v[98:101], v[16:31]
	ds_read_b128 v[248:251], v218 offset:16384
	v_mfma_f32_32x32x16_bf16 v[0:15], v[176:179], v[98:101], v[0:15]
	ds_read_b128 v[252:255], v219 offset:16384
	v_max_f32_e32 v98, v80, v80
	v_max_f32_e32 v97, v98, v97
	v_max3_f32 v97, v97, v82, v83
	v_max3_f32 v97, v97, v84, v85
	v_max3_f32 v97, v97, v86, v87
	v_max3_f32 v97, v97, v88, v89
	v_max3_f32 v97, v97, v90, v91
	v_max3_f32 v97, v97, v92, v93
	v_max3_f32 v97, v97, v94, v95
	ds_bpermute_b32 v98, v229, v97
	s_waitcnt lgkmcnt(0)
	v_max_f32_e32 v96, v98, v98
	v_max_f32_e32 v96, v97, v96
	v_cmp_lt_f32_e32 vcc, 0, v96
	s_cbranch_vccz .LBB0_861
	v_max_f32_e32 v96, v96, v96
	v_max_f32_e32 v96, 0, v96
	v_exp_f32_e64 v98, -v96
	v_pk_add_f32 v[80:81], v[80:81], v[96:97] op_sel_hi:[1,0] neg_lo:[0,1] neg_hi:[0,1]
	v_pk_add_f32 v[82:83], v[82:83], v[96:97] op_sel_hi:[1,0] neg_lo:[0,1] neg_hi:[0,1]
	v_pk_add_f32 v[84:85], v[84:85], v[96:97] op_sel_hi:[1,0] neg_lo:[0,1] neg_hi:[0,1]
	v_mul_f32_e32 v112, v112, v98
	v_pk_add_f32 v[86:87], v[86:87], v[96:97] op_sel_hi:[1,0] neg_lo:[0,1] neg_hi:[0,1]
	v_pk_add_f32 v[88:89], v[88:89], v[96:97] op_sel_hi:[1,0] neg_lo:[0,1] neg_hi:[0,1]
	v_pk_add_f32 v[90:91], v[90:91], v[96:97] op_sel_hi:[1,0] neg_lo:[0,1] neg_hi:[0,1]
	v_pk_add_f32 v[92:93], v[92:93], v[96:97] op_sel_hi:[1,0] neg_lo:[0,1] neg_hi:[0,1]
	v_sub_f32_e32 v79, v79, v96
	v_sub_f32_e32 v78, v78, v96
	v_sub_f32_e32 v77, v77, v96
	v_sub_f32_e32 v76, v76, v96
	v_sub_f32_e32 v75, v75, v96
	v_sub_f32_e32 v74, v74, v96
	v_sub_f32_e32 v73, v73, v96
	v_sub_f32_e32 v72, v72, v96
	v_sub_f32_e32 v71, v71, v96
	v_sub_f32_e32 v70, v70, v96
	v_sub_f32_e32 v69, v69, v96
	v_sub_f32_e32 v68, v68, v96
	v_sub_f32_e32 v67, v67, v96
	v_sub_f32_e32 v66, v66, v96
	v_sub_f32_e32 v65, v65, v96
	v_sub_f32_e32 v64, v64, v96
	v_pk_add_f32 v[94:95], v[94:95], v[96:97] op_sel_hi:[1,0] neg_lo:[0,1] neg_hi:[0,1]
	v_pk_mul_f32 v[62:63], v[62:63], v[98:99] op_sel_hi:[1,0]
	v_pk_mul_f32 v[60:61], v[60:61], v[98:99] op_sel_hi:[1,0]
	v_pk_mul_f32 v[58:59], v[58:59], v[98:99] op_sel_hi:[1,0]
	v_pk_mul_f32 v[56:57], v[56:57], v[98:99] op_sel_hi:[1,0]
	v_pk_mul_f32 v[54:55], v[54:55], v[98:99] op_sel_hi:[1,0]
	v_pk_mul_f32 v[52:53], v[52:53], v[98:99] op_sel_hi:[1,0]
	v_pk_mul_f32 v[50:51], v[50:51], v[98:99] op_sel_hi:[1,0]
	v_pk_mul_f32 v[48:49], v[48:49], v[98:99] op_sel_hi:[1,0]
	v_pk_mul_f32 v[46:47], v[46:47], v[98:99] op_sel_hi:[1,0]
	v_pk_mul_f32 v[44:45], v[44:45], v[98:99] op_sel_hi:[1,0]
	v_pk_mul_f32 v[42:43], v[42:43], v[98:99] op_sel_hi:[1,0]
	v_pk_mul_f32 v[40:41], v[40:41], v[98:99] op_sel_hi:[1,0]
	v_pk_mul_f32 v[38:39], v[38:39], v[98:99] op_sel_hi:[1,0]
	v_pk_mul_f32 v[36:37], v[36:37], v[98:99] op_sel_hi:[1,0]
	v_pk_mul_f32 v[34:35], v[34:35], v[98:99] op_sel_hi:[1,0]
	v_pk_mul_f32 v[32:33], v[32:33], v[98:99] op_sel_hi:[1,0]
	v_pk_mul_f32 v[30:31], v[30:31], v[98:99] op_sel_hi:[1,0]
	v_pk_mul_f32 v[28:29], v[28:29], v[98:99] op_sel_hi:[1,0]
	v_pk_mul_f32 v[26:27], v[26:27], v[98:99] op_sel_hi:[1,0]
	v_pk_mul_f32 v[24:25], v[24:25], v[98:99] op_sel_hi:[1,0]
	v_pk_mul_f32 v[22:23], v[22:23], v[98:99] op_sel_hi:[1,0]
	v_pk_mul_f32 v[20:21], v[20:21], v[98:99] op_sel_hi:[1,0]
	v_pk_mul_f32 v[18:19], v[18:19], v[98:99] op_sel_hi:[1,0]
	v_pk_mul_f32 v[16:17], v[16:17], v[98:99] op_sel_hi:[1,0]
	v_pk_mul_f32 v[14:15], v[14:15], v[98:99] op_sel_hi:[1,0]
	v_pk_mul_f32 v[12:13], v[12:13], v[98:99] op_sel_hi:[1,0]
	v_pk_mul_f32 v[10:11], v[10:11], v[98:99] op_sel_hi:[1,0]
	v_pk_mul_f32 v[8:9], v[8:9], v[98:99] op_sel_hi:[1,0]
	v_pk_mul_f32 v[6:7], v[6:7], v[98:99] op_sel_hi:[1,0]
	v_pk_mul_f32 v[4:5], v[4:5], v[98:99] op_sel_hi:[1,0]
	v_pk_mul_f32 v[2:3], v[2:3], v[98:99] op_sel_hi:[1,0]
	v_pk_mul_f32 v[0:1], v[0:1], v[98:99] op_sel_hi:[1,0]
.LBB0_861:
	v_exp_f32_e32 v113, v80
	v_exp_f32_e32 v122, v81
	v_exp_f32_e32 v123, v82
	v_mfma_f32_32x32x16_bf16 v[96:111], v[180:183], v[144:147], v[64:79]
	ds_read_b128 v[176:179], v220 offset:16384
	v_exp_f32_e32 v124, v83
	v_exp_f32_e32 v125, v84
	v_exp_f32_e32 v126, v85
	v_exp_f32_e32 v127, v86
	v_exp_f32_e32 v230, v87
	v_exp_f32_e32 v88, v88
	v_exp_f32_e32 v89, v89
	v_mfma_f32_32x32x16_bf16 v[96:111], v[236:239], v[156:159], v[96:111]
	ds_read_b128 v[180:183], v221 offset:16384
	v_exp_f32_e32 v90, v90
	v_exp_f32_e32 v91, v91
	v_exp_f32_e32 v92, v92
	v_exp_f32_e32 v93, v93
	v_exp_f32_e32 v94, v94
	v_exp_f32_e32 v95, v95
	v_mfma_f32_32x32x16_bf16 v[96:111], v[240:243], v[168:171], v[96:111]
	ds_read_b128 v[236:239], v205 offset:57344
	v_mfma_f32_32x32x16_bf16 v[96:111], v[244:247], v[172:175], v[96:111]
	ds_read_b128 v[240:243], v207 offset:57344
	v_mfma_f32_32x32x16_bf16 v[96:111], v[248:251], v[164:167], v[96:111]
	ds_read_b128 v[244:247], v209 offset:57344
	v_mfma_f32_32x32x16_bf16 v[96:111], v[252:255], v[160:163], v[96:111]
	ds_read_b128 v[248:251], v211 offset:57344
	s_waitcnt lgkmcnt(4)
	v_mfma_f32_32x32x16_bf16 v[96:111], v[176:179], v[152:155], v[96:111]
	ds_read_b128 v[252:255], v227
	v_mfma_f32_32x32x16_bf16 v[96:111], v[180:183], v[148:151], v[96:111]
	ds_read_b128 v[176:179], v227 offset:4096
	s_waitcnt lgkmcnt(4)
	v_mfma_f32_32x32x16_bf16 v[96:111], v[236:239], v[140:143], v[96:111]
	ds_read_b128 v[180:183], v227 offset:8192
	v_mfma_f32_32x32x16_bf16 v[96:111], v[240:243], v[136:139], v[96:111]
	ds_read_b128 v[236:239], v227 offset:12288
	s_waitcnt lgkmcnt(4)
	v_mfma_f32_32x32x16_bf16 v[96:111], v[244:247], v[132:135], v[96:111]
	ds_read_b128 v[240:243], v228 offset:4096
	v_cvt_pk_bf16_f32 v114, v113, v122
	v_cvt_pk_bf16_f32 v115, v123, v124
	v_cvt_pk_bf16_f32 v116, v125, v126
	v_cvt_pk_bf16_f32 v117, v127, v230
	v_mfma_f32_32x32x16_bf16 v[96:111], v[248:251], v[128:131], v[96:111]
	ds_read_b128 v[244:247], v228
	v_add_f32_e32 v118, 0, v113
	v_add_f32_e32 v113, v122, v118
	v_add_f32_e32 v113, v123, v113
	s_waitcnt lgkmcnt(4)
	v_mfma_f32_32x32x16_bf16 v[48:63], v[252:255], v[114:117], v[48:63]
	ds_read_b128 v[248:251], v228 offset:8192
	v_add_f32_e32 v80, v124, v113
	v_add_f32_e32 v80, v125, v80
	v_add_f32_e32 v80, v126, v80
	v_add_f32_e32 v113, v127, v80
	v_mfma_f32_32x32x16_bf16 v[32:47], v[176:179], v[114:117], v[32:47]
	ds_read_b128 v[252:255], v228 offset:12288
	v_add_f32_e32 v84, v230, v113
	v_add_f32_e32 v84, v88, v84
	v_add_f32_e32 v113, v89, v84
	s_waitcnt lgkmcnt(4)
	v_mfma_f32_32x32x16_bf16 v[16:31], v[180:183], v[114:117], v[16:31]
	ds_read_b128 v[176:179], v214 offset:24576
	v_add_f32_e32 v80, v90, v113
	v_add_f32_e32 v80, v91, v80
	v_add_f32_e32 v80, v92, v80
	v_add_f32_e32 v113, v93, v80
	v_add_f32_e32 v113, v94, v113
	v_mfma_f32_32x32x16_bf16 v[0:15], v[236:239], v[114:117], v[0:15]
	ds_read_b128 v[180:183], v215 offset:24576
	v_cvt_pk_bf16_f32 v84, v88, v89
	v_cvt_pk_bf16_f32 v85, v90, v91
	v_cvt_pk_bf16_f32 v86, v92, v93
	v_max_f32_e32 v92, v97, v97
	v_max_f32_e32 v93, v96, v96
	v_max_f32_e32 v92, v93, v92
	v_max3_f32 v92, v92, v98, v99
	v_max3_f32 v92, v92, v100, v101
	v_cvt_pk_bf16_f32 v87, v94, v95
	v_max3_f32 v92, v92, v102, v103
	v_add_f32_e32 v94, v95, v113
	s_waitcnt lgkmcnt(4)
	v_mfma_f32_32x32x16_bf16 v[32:47], v[240:243], v[84:87], v[32:47]
	ds_read_b128 v[236:239], v216 offset:24576
	v_max3_f32 v88, v92, v104, v105
	v_max3_f32 v88, v88, v106, v107
	v_max3_f32 v88, v88, v108, v109
	v_max3_f32 v92, v88, v110, v111
	ds_bpermute_b32 v93, v229, v92
	v_add_f32_e32 v112, v112, v94
	v_mfma_f32_32x32x16_bf16 v[48:63], v[244:247], v[84:87], v[48:63]
	ds_read_b128 v[240:243], v217 offset:24576
	s_waitcnt vmcnt(0)
	s_barrier
	s_waitcnt lgkmcnt(5)
	v_mfma_f32_32x32x16_bf16 v[16:31], v[248:251], v[84:87], v[16:31]
	ds_read_b128 v[244:247], v218 offset:24576
	s_waitcnt lgkmcnt(2)
	v_max_f32_e32 v80, v93, v93
	v_max_f32_e32 v80, v92, v80
	v_cmp_lt_f32_e32 vcc, 0, v80
	v_mfma_f32_32x32x16_bf16 v[0:15], v[252:255], v[84:87], v[0:15]
	ds_read_b128 v[248:251], v219 offset:24576
	s_cbranch_vccz .LBB0_863
	v_max_f32_e32 v80, v80, v80
	v_max_f32_e32 v80, 0, v80
	v_exp_f32_e64 v82, -v80
	v_pk_add_f32 v[96:97], v[96:97], v[80:81] op_sel_hi:[1,0] neg_lo:[0,1] neg_hi:[0,1]
	v_pk_add_f32 v[98:99], v[98:99], v[80:81] op_sel_hi:[1,0] neg_lo:[0,1] neg_hi:[0,1]
	v_pk_add_f32 v[100:101], v[100:101], v[80:81] op_sel_hi:[1,0] neg_lo:[0,1] neg_hi:[0,1]
	v_mul_f32_e32 v112, v112, v82
	v_pk_add_f32 v[102:103], v[102:103], v[80:81] op_sel_hi:[1,0] neg_lo:[0,1] neg_hi:[0,1]
	v_pk_add_f32 v[104:105], v[104:105], v[80:81] op_sel_hi:[1,0] neg_lo:[0,1] neg_hi:[0,1]
	v_pk_add_f32 v[106:107], v[106:107], v[80:81] op_sel_hi:[1,0] neg_lo:[0,1] neg_hi:[0,1]
	v_pk_add_f32 v[108:109], v[108:109], v[80:81] op_sel_hi:[1,0] neg_lo:[0,1] neg_hi:[0,1]
	v_sub_f32_e32 v79, v79, v80
	v_sub_f32_e32 v78, v78, v80
	v_sub_f32_e32 v77, v77, v80
	v_sub_f32_e32 v76, v76, v80
	v_sub_f32_e32 v75, v75, v80
	v_sub_f32_e32 v74, v74, v80
	v_sub_f32_e32 v73, v73, v80
	v_sub_f32_e32 v72, v72, v80
	v_sub_f32_e32 v71, v71, v80
	v_sub_f32_e32 v70, v70, v80
	v_sub_f32_e32 v69, v69, v80
	v_sub_f32_e32 v68, v68, v80
	v_sub_f32_e32 v67, v67, v80
	v_sub_f32_e32 v66, v66, v80
	v_sub_f32_e32 v65, v65, v80
	v_sub_f32_e32 v64, v64, v80
	v_pk_add_f32 v[110:111], v[110:111], v[80:81] op_sel_hi:[1,0] neg_lo:[0,1] neg_hi:[0,1]
	v_pk_mul_f32 v[62:63], v[62:63], v[82:83] op_sel_hi:[1,0]
	v_pk_mul_f32 v[60:61], v[60:61], v[82:83] op_sel_hi:[1,0]
	v_pk_mul_f32 v[58:59], v[58:59], v[82:83] op_sel_hi:[1,0]
	v_pk_mul_f32 v[56:57], v[56:57], v[82:83] op_sel_hi:[1,0]
	v_pk_mul_f32 v[54:55], v[54:55], v[82:83] op_sel_hi:[1,0]
	v_pk_mul_f32 v[52:53], v[52:53], v[82:83] op_sel_hi:[1,0]
	v_pk_mul_f32 v[50:51], v[50:51], v[82:83] op_sel_hi:[1,0]
	v_pk_mul_f32 v[48:49], v[48:49], v[82:83] op_sel_hi:[1,0]
	v_pk_mul_f32 v[46:47], v[46:47], v[82:83] op_sel_hi:[1,0]
	v_pk_mul_f32 v[44:45], v[44:45], v[82:83] op_sel_hi:[1,0]
	v_pk_mul_f32 v[42:43], v[42:43], v[82:83] op_sel_hi:[1,0]
	v_pk_mul_f32 v[40:41], v[40:41], v[82:83] op_sel_hi:[1,0]
	v_pk_mul_f32 v[38:39], v[38:39], v[82:83] op_sel_hi:[1,0]
	v_pk_mul_f32 v[36:37], v[36:37], v[82:83] op_sel_hi:[1,0]
	v_pk_mul_f32 v[34:35], v[34:35], v[82:83] op_sel_hi:[1,0]
	v_pk_mul_f32 v[32:33], v[32:33], v[82:83] op_sel_hi:[1,0]
	v_pk_mul_f32 v[30:31], v[30:31], v[82:83] op_sel_hi:[1,0]
	v_pk_mul_f32 v[28:29], v[28:29], v[82:83] op_sel_hi:[1,0]
	v_pk_mul_f32 v[26:27], v[26:27], v[82:83] op_sel_hi:[1,0]
	v_pk_mul_f32 v[24:25], v[24:25], v[82:83] op_sel_hi:[1,0]
	v_pk_mul_f32 v[22:23], v[22:23], v[82:83] op_sel_hi:[1,0]
	v_pk_mul_f32 v[20:21], v[20:21], v[82:83] op_sel_hi:[1,0]
	v_pk_mul_f32 v[18:19], v[18:19], v[82:83] op_sel_hi:[1,0]
	v_pk_mul_f32 v[16:17], v[16:17], v[82:83] op_sel_hi:[1,0]
	v_pk_mul_f32 v[14:15], v[14:15], v[82:83] op_sel_hi:[1,0]
	v_pk_mul_f32 v[12:13], v[12:13], v[82:83] op_sel_hi:[1,0]
	v_pk_mul_f32 v[10:11], v[10:11], v[82:83] op_sel_hi:[1,0]
	v_pk_mul_f32 v[8:9], v[8:9], v[82:83] op_sel_hi:[1,0]
	v_pk_mul_f32 v[6:7], v[6:7], v[82:83] op_sel_hi:[1,0]
	v_pk_mul_f32 v[4:5], v[4:5], v[82:83] op_sel_hi:[1,0]
	v_pk_mul_f32 v[2:3], v[2:3], v[82:83] op_sel_hi:[1,0]
	v_pk_mul_f32 v[0:1], v[0:1], v[82:83] op_sel_hi:[1,0]

.Lmla_dma_skip_t1:
	v_cvt_pk_bf16_f32 v124, v100, v101
	v_cvt_pk_bf16_f32 v125, v102, v103
	v_exp_f32_e32 v104, v104
	v_exp_f32_e32 v105, v105
	v_exp_f32_e32 v106, v106
	v_exp_f32_e32 v107, v107
	v_mfma_f32_32x32x16_bf16 v[80:95], v[236:239], v[168:171], v[80:95]
	ds_read_b128 v[180:183], v205 offset:61440
	v_exp_f32_e32 v108, v108
	v_exp_f32_e32 v109, v109
	v_exp_f32_e32 v110, v110
	v_exp_f32_e32 v111, v111
	s_add_i32 s16, s8, 3
	s_cmp_lt_u32 s16, s9
	s_cselect_b64 s[10:11], -1, 0
	s_waitcnt lgkmcnt(4)
	v_mfma_f32_32x32x16_bf16 v[80:95], v[240:243], v[172:175], v[80:95]
	ds_read_b128 v[236:239], v207 offset:61440
	s_cmp_ge_u32 s16, s9
	v_mfma_f32_32x32x16_bf16 v[80:95], v[244:247], v[164:167], v[80:95]
	ds_read_b128 v[240:243], v209 offset:61440
	s_waitcnt lgkmcnt(4)
	v_mfma_f32_32x32x16_bf16 v[80:95], v[248:251], v[160:163], v[80:95]
	ds_read_b128 v[244:247], v211 offset:61440
	v_mfma_f32_32x32x16_bf16 v[80:95], v[252:255], v[152:155], v[80:95]
	ds_read_b128 v[248:251], v225 offset:16384
	s_waitcnt lgkmcnt(4)
	v_mfma_f32_32x32x16_bf16 v[80:95], v[176:179], v[148:151], v[80:95]
	ds_read_b128 v[252:255], v225 offset:20480
	v_mfma_f32_32x32x16_bf16 v[80:95], v[180:183], v[140:143], v[80:95]
	ds_read_b128 v[176:179], v225 offset:24576
	s_waitcnt lgkmcnt(4)
	v_mfma_f32_32x32x16_bf16 v[80:95], v[236:239], v[136:139], v[80:95]
	ds_read_b128 v[180:183], v225 offset:28672
	v_mfma_f32_32x32x16_bf16 v[80:95], v[240:243], v[132:135], v[80:95]
	ds_read_b128 v[236:239], v226 offset:16384
	s_waitcnt lgkmcnt(4)
	v_mfma_f32_32x32x16_bf16 v[80:95], v[244:247], v[128:131], v[80:95]
	ds_read_b128 v[240:243], v226 offset:20480
	v_mfma_f32_32x32x16_bf16 v[48:63], v[248:251], v[122:125], v[48:63]
	ds_read_b128 v[244:247], v226 offset:24576
	s_nop 8
	v_max_f32_e32 v113, v81, v81
	v_max_f32_e32 v126, v80, v80
	v_max_f32_e32 v113, v126, v113
	v_max3_f32 v113, v113, v82, v83
	v_max3_f32 v113, v113, v84, v85
	v_max3_f32 v113, v113, v86, v87
	v_max3_f32 v113, v113, v88, v89
	s_waitcnt lgkmcnt(4)
	v_mfma_f32_32x32x16_bf16 v[32:47], v[252:255], v[122:125], v[32:47]
	ds_read_b128 v[248:251], v226 offset:28672
	v_max3_f32 v113, v113, v90, v91
	v_max3_f32 v113, v113, v92, v93
	v_max3_f32 v113, v113, v94, v95
	v_mfma_f32_32x32x16_bf16 v[16:31], v[176:179], v[122:125], v[16:31]
	ds_read_b128 v[252:255], v214 offset:32768
	s_waitcnt lgkmcnt(4)
	v_mfma_f32_32x32x16_bf16 v[0:15], v[180:183], v[122:125], v[0:15]
	ds_read_b128 v[176:179], v215 offset:32768
	v_cvt_pk_bf16_f32 v118, v104, v105
	v_cvt_pk_bf16_f32 v119, v106, v107
	v_cvt_pk_bf16_f32 v120, v108, v109
	v_cvt_pk_bf16_f32 v121, v110, v111
	s_nop 0
	s_nop 0
	v_mfma_f32_32x32x16_bf16 v[48:63], v[236:239], v[118:121], v[48:63]
	ds_read_b128 v[180:183], v216 offset:32768
	s_waitcnt lgkmcnt(4)
	v_mfma_f32_32x32x16_bf16 v[32:47], v[240:243], v[118:121], v[32:47]
	ds_read_b128 v[236:239], v217 offset:32768
	v_mfma_f32_32x32x16_bf16 v[16:31], v[244:247], v[118:121], v[16:31]
	ds_read_b128 v[240:243], v218 offset:32768
	ds_bpermute_b32 v114, v229, v113
	s_waitcnt lgkmcnt(5)
	v_mfma_f32_32x32x16_bf16 v[0:15], v[248:251], v[118:121], v[0:15]
	ds_read_b128 v[244:247], v219 offset:32768

.LBB0_867:
	v_exp_f32_e32 v113, v80
	v_exp_f32_e32 v122, v81
	v_exp_f32_e32 v123, v82
	v_mfma_f32_32x32x16_bf16 v[96:111], v[252:255], v[144:147], v[64:79]
	ds_read_b128 v[248:251], v220 offset:32768
	v_exp_f32_e32 v124, v83
	v_exp_f32_e32 v125, v84
	v_exp_f32_e32 v126, v85
	v_exp_f32_e32 v127, v86
	v_exp_f32_e32 v230, v87
	v_exp_f32_e32 v88, v88
	v_exp_f32_e32 v89, v89
	v_mfma_f32_32x32x16_bf16 v[96:111], v[176:179], v[156:159], v[96:111]
	ds_read_b128 v[252:255], v221 offset:32768
	v_exp_f32_e32 v90, v90
	v_exp_f32_e32 v91, v91
	v_exp_f32_e32 v92, v92
	v_exp_f32_e32 v93, v93
	v_exp_f32_e32 v94, v94
	v_exp_f32_e32 v95, v95
	v_mfma_f32_32x32x16_bf16 v[96:111], v[180:183], v[168:171], v[96:111]
	ds_read_b128 v[176:179], v206 offset:16384
	v_mfma_f32_32x32x16_bf16 v[96:111], v[236:239], v[172:175], v[96:111]
	ds_read_b128 v[180:183], v208 offset:16384
	v_mfma_f32_32x32x16_bf16 v[96:111], v[240:243], v[164:167], v[96:111]
	ds_read_b128 v[236:239], v210 offset:16384
	s_waitcnt lgkmcnt(4)
	v_mfma_f32_32x32x16_bf16 v[96:111], v[244:247], v[160:163], v[96:111]
	ds_read_b128 v[240:243], v212 offset:16384
	v_mfma_f32_32x32x16_bf16 v[96:111], v[248:251], v[152:155], v[96:111]
	ds_read_b128 v[244:247], v227 offset:16384
	s_waitcnt lgkmcnt(4)
	v_mfma_f32_32x32x16_bf16 v[96:111], v[252:255], v[148:151], v[96:111]
	ds_read_b128 v[248:251], v227 offset:20480
	v_mfma_f32_32x32x16_bf16 v[96:111], v[176:179], v[140:143], v[96:111]
	ds_read_b128 v[252:255], v227 offset:24576
	s_waitcnt lgkmcnt(4)
	v_mfma_f32_32x32x16_bf16 v[96:111], v[180:183], v[136:139], v[96:111]
	ds_read_b128 v[176:179], v227 offset:28672
	v_mfma_f32_32x32x16_bf16 v[96:111], v[236:239], v[132:135], v[96:111]
	ds_read_b128 v[180:183], v228 offset:20480
	v_cvt_pk_bf16_f32 v114, v113, v122
	v_cvt_pk_bf16_f32 v115, v123, v124
	v_cvt_pk_bf16_f32 v116, v125, v126
	v_cvt_pk_bf16_f32 v117, v127, v230
	s_waitcnt lgkmcnt(4)
	v_mfma_f32_32x32x16_bf16 v[96:111], v[240:243], v[128:131], v[96:111]
	ds_read_b128 v[236:239], v228 offset:16384
	v_add_f32_e32 v118, 0, v113
	v_add_f32_e32 v113, v122, v118
	v_add_f32_e32 v113, v123, v113
	v_mfma_f32_32x32x16_bf16 v[48:63], v[244:247], v[114:117], v[48:63]
	ds_read_b128 v[240:243], v228 offset:24576
	v_add_f32_e32 v80, v124, v113
	v_add_f32_e32 v80, v125, v80
	v_add_f32_e32 v80, v126, v80
	v_add_f32_e32 v113, v127, v80
	s_waitcnt lgkmcnt(4)
	v_mfma_f32_32x32x16_bf16 v[32:47], v[248:251], v[114:117], v[32:47]
	ds_read_b128 v[244:247], v228 offset:28672
	v_add_f32_e32 v84, v230, v113
	v_add_f32_e32 v84, v88, v84
	v_add_f32_e32 v113, v89, v84
	v_mfma_f32_32x32x16_bf16 v[16:31], v[252:255], v[114:117], v[16:31]
	ds_read_b128 v[248:251], v214 offset:40960
	v_add_f32_e32 v80, v90, v113
	v_add_f32_e32 v80, v91, v80
	v_add_f32_e32 v80, v92, v80
	v_add_f32_e32 v113, v93, v80
	v_add_f32_e32 v113, v94, v113
	s_waitcnt lgkmcnt(4)
	v_mfma_f32_32x32x16_bf16 v[0:15], v[176:179], v[114:117], v[0:15]
	ds_read_b128 v[252:255], v215 offset:40960
	v_cvt_pk_bf16_f32 v84, v88, v89
	v_cvt_pk_bf16_f32 v85, v90, v91
	v_cvt_pk_bf16_f32 v86, v92, v93
	v_max_f32_e32 v92, v97, v97
	v_max_f32_e32 v93, v96, v96
	v_max_f32_e32 v92, v93, v92
	v_max3_f32 v92, v92, v98, v99
	v_max3_f32 v92, v92, v100, v101
	v_cvt_pk_bf16_f32 v87, v94, v95
	v_max3_f32 v92, v92, v102, v103
	v_add_f32_e32 v94, v95, v113
	v_mfma_f32_32x32x16_bf16 v[32:47], v[180:183], v[84:87], v[32:47]
	ds_read_b128 v[176:179], v216 offset:40960
	v_max3_f32 v88, v92, v104, v105
	v_max3_f32 v88, v88, v106, v107
	v_max3_f32 v88, v88, v108, v109
	v_max3_f32 v92, v88, v110, v111
	ds_bpermute_b32 v93, v229, v92
	v_add_f32_e32 v112, v112, v94
	s_waitcnt lgkmcnt(5)
	v_mfma_f32_32x32x16_bf16 v[48:63], v[236:239], v[84:87], v[48:63]
	ds_read_b128 v[180:183], v217 offset:40960
	s_waitcnt vmcnt(0)
	s_barrier
	v_mfma_f32_32x32x16_bf16 v[16:31], v[240:243], v[84:87], v[16:31]
	ds_read_b128 v[236:239], v218 offset:40960
	s_waitcnt lgkmcnt(2)
	v_max_f32_e32 v80, v93, v93
	v_max_f32_e32 v80, v92, v80
	v_cmp_lt_f32_e32 vcc, 0, v80
	v_mfma_f32_32x32x16_bf16 v[0:15], v[244:247], v[84:87], v[0:15]
	ds_read_b128 v[240:243], v219 offset:40960
	s_cbranch_vccz .LBB0_869
	v_max_f32_e32 v80, v80, v80
	v_max_f32_e32 v80, 0, v80
	v_exp_f32_e64 v82, -v80
	v_pk_add_f32 v[96:97], v[96:97], v[80:81] op_sel_hi:[1,0] neg_lo:[0,1] neg_hi:[0,1]
	v_pk_add_f32 v[98:99], v[98:99], v[80:81] op_sel_hi:[1,0] neg_lo:[0,1] neg_hi:[0,1]
	v_pk_add_f32 v[100:101], v[100:101], v[80:81] op_sel_hi:[1,0] neg_lo:[0,1] neg_hi:[0,1]
	v_mul_f32_e32 v112, v112, v82
	v_pk_add_f32 v[102:103], v[102:103], v[80:81] op_sel_hi:[1,0] neg_lo:[0,1] neg_hi:[0,1]
	v_pk_add_f32 v[104:105], v[104:105], v[80:81] op_sel_hi:[1,0] neg_lo:[0,1] neg_hi:[0,1]
	v_pk_add_f32 v[106:107], v[106:107], v[80:81] op_sel_hi:[1,0] neg_lo:[0,1] neg_hi:[0,1]
	v_pk_add_f32 v[108:109], v[108:109], v[80:81] op_sel_hi:[1,0] neg_lo:[0,1] neg_hi:[0,1]
	v_sub_f32_e32 v79, v79, v80
	v_sub_f32_e32 v78, v78, v80
	v_sub_f32_e32 v77, v77, v80
	v_sub_f32_e32 v76, v76, v80
	v_sub_f32_e32 v75, v75, v80
	v_sub_f32_e32 v74, v74, v80
	v_sub_f32_e32 v73, v73, v80
	v_sub_f32_e32 v72, v72, v80
	v_sub_f32_e32 v71, v71, v80
	v_sub_f32_e32 v70, v70, v80
	v_sub_f32_e32 v69, v69, v80
	v_sub_f32_e32 v68, v68, v80
	v_sub_f32_e32 v67, v67, v80
	v_sub_f32_e32 v66, v66, v80
	v_sub_f32_e32 v65, v65, v80
	v_sub_f32_e32 v64, v64, v80
	v_pk_add_f32 v[110:111], v[110:111], v[80:81] op_sel_hi:[1,0] neg_lo:[0,1] neg_hi:[0,1]
	v_pk_mul_f32 v[62:63], v[62:63], v[82:83] op_sel_hi:[1,0]
	v_pk_mul_f32 v[60:61], v[60:61], v[82:83] op_sel_hi:[1,0]
	v_pk_mul_f32 v[58:59], v[58:59], v[82:83] op_sel_hi:[1,0]
	v_pk_mul_f32 v[56:57], v[56:57], v[82:83] op_sel_hi:[1,0]
	v_pk_mul_f32 v[54:55], v[54:55], v[82:83] op_sel_hi:[1,0]
	v_pk_mul_f32 v[52:53], v[52:53], v[82:83] op_sel_hi:[1,0]
	v_pk_mul_f32 v[50:51], v[50:51], v[82:83] op_sel_hi:[1,0]
	v_pk_mul_f32 v[48:49], v[48:49], v[82:83] op_sel_hi:[1,0]
	v_pk_mul_f32 v[46:47], v[46:47], v[82:83] op_sel_hi:[1,0]
	v_pk_mul_f32 v[44:45], v[44:45], v[82:83] op_sel_hi:[1,0]
	v_pk_mul_f32 v[42:43], v[42:43], v[82:83] op_sel_hi:[1,0]
	v_pk_mul_f32 v[40:41], v[40:41], v[82:83] op_sel_hi:[1,0]
	v_pk_mul_f32 v[38:39], v[38:39], v[82:83] op_sel_hi:[1,0]
	v_pk_mul_f32 v[36:37], v[36:37], v[82:83] op_sel_hi:[1,0]
	v_pk_mul_f32 v[34:35], v[34:35], v[82:83] op_sel_hi:[1,0]
	v_pk_mul_f32 v[32:33], v[32:33], v[82:83] op_sel_hi:[1,0]
	v_pk_mul_f32 v[30:31], v[30:31], v[82:83] op_sel_hi:[1,0]
	v_pk_mul_f32 v[28:29], v[28:29], v[82:83] op_sel_hi:[1,0]
	v_pk_mul_f32 v[26:27], v[26:27], v[82:83] op_sel_hi:[1,0]
	v_pk_mul_f32 v[24:25], v[24:25], v[82:83] op_sel_hi:[1,0]
	v_pk_mul_f32 v[22:23], v[22:23], v[82:83] op_sel_hi:[1,0]
	v_pk_mul_f32 v[20:21], v[20:21], v[82:83] op_sel_hi:[1,0]
	v_pk_mul_f32 v[18:19], v[18:19], v[82:83] op_sel_hi:[1,0]
	v_pk_mul_f32 v[16:17], v[16:17], v[82:83] op_sel_hi:[1,0]
	v_pk_mul_f32 v[14:15], v[14:15], v[82:83] op_sel_hi:[1,0]
	v_pk_mul_f32 v[12:13], v[12:13], v[82:83] op_sel_hi:[1,0]
	v_pk_mul_f32 v[10:11], v[10:11], v[82:83] op_sel_hi:[1,0]
	v_pk_mul_f32 v[8:9], v[8:9], v[82:83] op_sel_hi:[1,0]
	v_pk_mul_f32 v[6:7], v[6:7], v[82:83] op_sel_hi:[1,0]
	v_pk_mul_f32 v[4:5], v[4:5], v[82:83] op_sel_hi:[1,0]
	v_pk_mul_f32 v[2:3], v[2:3], v[82:83] op_sel_hi:[1,0]
	v_pk_mul_f32 v[0:1], v[0:1], v[82:83] op_sel_hi:[1,0]

.Lmla_dma_skip_t2:
	v_cvt_pk_bf16_f32 v124, v100, v101
	v_cvt_pk_bf16_f32 v125, v102, v103
	v_exp_f32_e32 v104, v104
	v_exp_f32_e32 v105, v105
	v_exp_f32_e32 v106, v106
	v_exp_f32_e32 v107, v107
	v_mfma_f32_32x32x16_bf16 v[80:95], v[176:179], v[168:171], v[80:95]
	ds_read_b128 v[252:255], v206 offset:20480
	v_exp_f32_e32 v108, v108
	v_exp_f32_e32 v109, v109
	v_exp_f32_e32 v110, v110
	v_exp_f32_e32 v111, v111
	s_add_i32 s4, s8, 4
	s_cmp_ge_u32 s4, s9
	s_waitcnt lgkmcnt(4)
	v_mfma_f32_32x32x16_bf16 v[80:95], v[180:183], v[172:175], v[80:95]
	ds_read_b128 v[176:179], v208 offset:20480
	v_mfma_f32_32x32x16_bf16 v[80:95], v[236:239], v[164:167], v[80:95]
	ds_read_b128 v[180:183], v210 offset:20480
	s_waitcnt lgkmcnt(4)
	v_mfma_f32_32x32x16_bf16 v[80:95], v[240:243], v[160:163], v[80:95]
	ds_read_b128 v[236:239], v212 offset:20480
	v_mfma_f32_32x32x16_bf16 v[80:95], v[244:247], v[152:155], v[80:95]
	ds_read_b128 v[240:243], v225 offset:32768
	s_waitcnt lgkmcnt(4)
	v_mfma_f32_32x32x16_bf16 v[80:95], v[248:251], v[148:151], v[80:95]
	ds_read_b128 v[244:247], v225 offset:36864
	v_mfma_f32_32x32x16_bf16 v[80:95], v[252:255], v[140:143], v[80:95]
	ds_read_b128 v[248:251], v225 offset:40960
	s_waitcnt lgkmcnt(4)
	v_mfma_f32_32x32x16_bf16 v[80:95], v[176:179], v[136:139], v[80:95]
	ds_read_b128 v[252:255], v225 offset:45056
	v_mfma_f32_32x32x16_bf16 v[80:95], v[180:183], v[132:135], v[80:95]
	ds_read_b128 v[176:179], v226 offset:32768
	s_waitcnt lgkmcnt(4)
	v_mfma_f32_32x32x16_bf16 v[80:95], v[236:239], v[128:131], v[80:95]
	ds_read_b128 v[180:183], v226 offset:36864
	v_mfma_f32_32x32x16_bf16 v[48:63], v[240:243], v[122:125], v[48:63]
	ds_read_b128 v[236:239], v226 offset:40960
	s_nop 8
	v_max_f32_e32 v113, v81, v81
	v_max_f32_e32 v126, v80, v80
	v_max_f32_e32 v113, v126, v113
	v_max3_f32 v113, v113, v82, v83
	v_max3_f32 v113, v113, v84, v85
	v_max3_f32 v113, v113, v86, v87
	v_max3_f32 v113, v113, v88, v89
	s_waitcnt lgkmcnt(4)
	v_mfma_f32_32x32x16_bf16 v[32:47], v[244:247], v[122:125], v[32:47]
	ds_read_b128 v[240:243], v226 offset:45056
	v_max3_f32 v113, v113, v90, v91
	v_max3_f32 v113, v113, v92, v93
	v_max3_f32 v113, v113, v94, v95
	v_mfma_f32_32x32x16_bf16 v[16:31], v[248:251], v[122:125], v[16:31]
	ds_read_b128 v[244:247], v214
	s_waitcnt lgkmcnt(4)
	v_mfma_f32_32x32x16_bf16 v[0:15], v[252:255], v[122:125], v[0:15]
	ds_read_b128 v[248:251], v215
	v_cvt_pk_bf16_f32 v118, v104, v105
	v_cvt_pk_bf16_f32 v119, v106, v107
	v_cvt_pk_bf16_f32 v120, v108, v109
	v_cvt_pk_bf16_f32 v121, v110, v111
	s_nop 0
	s_nop 0
	v_mfma_f32_32x32x16_bf16 v[48:63], v[176:179], v[118:121], v[48:63]
	ds_read_b128 v[252:255], v216
	s_waitcnt lgkmcnt(4)
	v_mfma_f32_32x32x16_bf16 v[32:47], v[180:183], v[118:121], v[32:47]
	ds_read_b128 v[176:179], v217
	v_mfma_f32_32x32x16_bf16 v[16:31], v[236:239], v[118:121], v[16:31]
	ds_read_b128 v[180:183], v218
	ds_bpermute_b32 v114, v229, v113
	s_waitcnt lgkmcnt(5)
	v_mfma_f32_32x32x16_bf16 v[0:15], v[240:243], v[118:121], v[0:15]
	ds_read_b128 v[236:239], v219

.LBB0_873:
	v_exp_f32_e32 v113, v80
	v_exp_f32_e32 v126, v85
	v_exp_f32_e32 v127, v86
	v_mfma_f32_32x32x16_bf16 v[96:111], v[244:247], v[144:147], v[64:79]
	ds_read_b128 v[240:243], v220
	v_add_f32_e32 v231, 0, v113
	v_exp_f32_e32 v230, v87
	v_exp_f32_e32 v88, v88
	v_exp_f32_e32 v89, v89
	v_exp_f32_e32 v90, v90
	v_exp_f32_e32 v91, v91
	v_exp_f32_e32 v92, v92
	v_mfma_f32_32x32x16_bf16 v[96:111], v[248:251], v[156:159], v[96:111]
	ds_read_b128 v[244:247], v221
	v_exp_f32_e32 v93, v93
	s_add_u32 s62, s62, 0x180
	s_addc_u32 s61, s61, 0
	s_add_u32 s60, s60, 0x12000
	s_addc_u32 s59, s59, 0
	s_add_i32 s4, s16, 3
	v_mfma_f32_32x32x16_bf16 v[96:111], v[252:255], v[168:171], v[96:111]
	ds_read_b128 v[248:251], v206
	s_cmp_le_u32 s4, s9
	v_mfma_f32_32x32x16_bf16 v[96:111], v[176:179], v[172:175], v[96:111]
	ds_read_b128 v[252:255], v208
	v_mfma_f32_32x32x16_bf16 v[96:111], v[180:183], v[164:167], v[96:111]
	ds_read_b128 v[176:179], v210
	s_waitcnt lgkmcnt(4)
	v_mfma_f32_32x32x16_bf16 v[96:111], v[236:239], v[160:163], v[96:111]
	ds_read_b128 v[180:183], v212
	v_mfma_f32_32x32x16_bf16 v[96:111], v[240:243], v[152:155], v[96:111]
	ds_read_b128 v[236:239], v227 offset:32768
	s_waitcnt lgkmcnt(4)
	v_mfma_f32_32x32x16_bf16 v[96:111], v[244:247], v[148:151], v[96:111]
	ds_read_b128 v[240:243], v227 offset:36864
	v_mfma_f32_32x32x16_bf16 v[96:111], v[248:251], v[140:143], v[96:111]
	ds_read_b128 v[244:247], v227 offset:40960
	s_waitcnt lgkmcnt(4)
	v_mfma_f32_32x32x16_bf16 v[96:111], v[252:255], v[136:139], v[96:111]
	ds_read_b128 v[248:251], v227 offset:45056
	v_exp_f32_e32 v118, v81
	v_exp_f32_e32 v119, v82
	v_exp_f32_e32 v120, v83
	v_exp_f32_e32 v121, v84
	v_mfma_f32_32x32x16_bf16 v[96:111], v[176:179], v[132:135], v[96:111]
	ds_read_b128 v[252:255], v228 offset:36864
	v_cvt_pk_bf16_f32 v114, v113, v118
	v_add_f32_e32 v113, v118, v231
	v_add_f32_e32 v113, v119, v113
	v_add_f32_e32 v113, v120, v113
	v_add_f32_e32 v113, v121, v113
	v_cvt_pk_bf16_f32 v115, v119, v120
	v_cvt_pk_bf16_f32 v116, v121, v126
	v_cvt_pk_bf16_f32 v117, v127, v230
	v_add_f32_e32 v113, v126, v113
	s_waitcnt lgkmcnt(4)
	v_mfma_f32_32x32x16_bf16 v[96:111], v[180:183], v[128:131], v[96:111]
	ds_read_b128 v[176:179], v228 offset:32768
	v_exp_f32_e32 v118, v94
	v_exp_f32_e32 v119, v95
	v_mfma_f32_32x32x16_bf16 v[48:63], v[236:239], v[114:117], v[48:63]
	ds_read_b128 v[180:183], v228 offset:40960
	v_add_f32_e32 v80, v127, v113
	v_add_f32_e32 v80, v230, v80
	v_add_f32_e32 v113, v88, v80
	v_cvt_pk_bf16_f32 v88, v88, v89
	s_waitcnt lgkmcnt(4)
	v_mfma_f32_32x32x16_bf16 v[32:47], v[240:243], v[114:117], v[32:47]
	ds_read_b128 v[236:239], v228 offset:45056
	v_add_f32_e32 v84, v89, v113
	v_add_f32_e32 v84, v90, v84
	v_add_f32_e32 v84, v91, v84
	v_add_f32_e32 v113, v92, v84
	v_add_f32_e32 v113, v93, v113
	v_cvt_pk_bf16_f32 v89, v90, v91
	v_mfma_f32_32x32x16_bf16 v[16:31], v[244:247], v[114:117], v[16:31]
	v_cvt_pk_bf16_f32 v90, v92, v93
	v_cvt_pk_bf16_f32 v91, v118, v119
	s_waitcnt lgkmcnt(3)
	v_mfma_f32_32x32x16_bf16 v[0:15], v[248:251], v[114:117], v[0:15]
	v_max_f32_e32 v114, v97, v97
	v_max_f32_e32 v115, v96, v96
	v_max_f32_e32 v114, v115, v114
	v_max3_f32 v114, v114, v98, v99
	v_mfma_f32_32x32x16_bf16 v[32:47], v[252:255], v[88:91], v[32:47]
	s_waitcnt vmcnt(0)
	s_barrier
	s_waitcnt lgkmcnt(2)
	v_mfma_f32_32x32x16_bf16 v[48:63], v[176:179], v[88:91], v[48:63]
	v_max3_f32 v80, v114, v100, v101
	v_max3_f32 v80, v80, v102, v103
	v_max3_f32 v80, v80, v104, v105
	v_max3_f32 v80, v80, v106, v107
	v_max3_f32 v80, v80, v108, v109
	v_max3_f32 v80, v80, v110, v111
	ds_bpermute_b32 v81, v229, v80
	s_waitcnt lgkmcnt(2)
	v_mfma_f32_32x32x16_bf16 v[16:31], v[180:183], v[88:91], v[16:31]
	v_add_f32_e32 v82, v118, v113
	v_add_f32_e32 v82, v119, v82
	v_add_f32_e32 v230, v112, v82
	s_waitcnt lgkmcnt(0)
	v_max_f32_e32 v81, v81, v81
	v_max_f32_e32 v82, v80, v81
	v_mfma_f32_32x32x16_bf16 v[0:15], v[236:239], v[88:91], v[0:15]
	s_cbranch_scc0 .LBB0_875
	s_mov_b32 s8, s16
	v_cmp_lt_f32_e32 vcc, 0, v82
	s_cbranch_vccnz .LBB0_858
	s_branch .LBB0_859
